# kfix tail: KPER/cos/sin loads issued with the row prefetch at token top, gkp loaded once
# speedup vs baseline: 1.0041x; 1.0039x over previous
.LBB0_319:
	s_or_b64 exec, exec, s[0:1]
	s_and_b64 vcc, exec, s[78:79]
	s_waitcnt lgkmcnt(0)
	s_barrier
	s_cbranch_vccnz .LBB0_376
	v_mov_b32_e32 v3, v206
	v_readlane_b32 s0, v254, 19
	v_ashrrev_i32_e32 v0, 6, v3
	s_nop 0
	v_add_u32_e32 v2, s0, v0
	v_mov_b32_e32 v0, s8
	v_add_co_u32_e32 v4, vcc, 0xd0000, v0
	v_mov_b32_e32 v0, s9
	s_nop 0
	v_addc_co_u32_e32 v5, vcc, 0, v0, vcc
	global_load_dwordx2 v[6:7], v[4:5], off offset:80 sc1
	s_movk_i32 s0, 0x4000
	global_load_dwordx2 v[4:5], v[4:5], off offset:88 sc1
	v_cmp_gt_i32_e32 vcc, s0, v2
	s_waitcnt vmcnt(0) lgkmcnt(0)
	v_readfirstlane_b32 s5, v7
	v_readfirstlane_b32 s4, v6
	v_readfirstlane_b32 s13, v5
	v_readfirstlane_b32 s12, v4
	s_and_saveexec_b64 s[0:1], vcc
	v_readlane_b32 s14, v255, 60
	v_readlane_b32 s18, v255, 62
	v_readlane_b32 s30, v254, 0
	s_movk_i32 s10, 0x7fff
	v_readlane_b32 s15, v255, 61
	v_readlane_b32 s19, v255, 63
	v_readlane_b32 s31, v254, 1
	s_cbranch_execz .LBB0_323
	v_and_b32_e32 v4, 64, v228
	v_xor_b32_e32 v0, 1, v228
	v_add_u32_e32 v8, 64, v4
	v_cmp_lt_i32_e32 vcc, v0, v8
	v_and_b32_e32 v16, 63, v3
	v_and_b32_e32 v9, 31, v3
	v_cndmask_b32_e32 v0, v228, v0, vcc
	v_lshlrev_b32_e32 v26, 2, v0
	v_xor_b32_e32 v0, 2, v228
	v_cmp_lt_i32_e32 vcc, v0, v8
	v_cmp_gt_u32_e64 s[36:37], 32, v16
	s_nop 0
	v_cndmask_b32_e32 v0, v228, v0, vcc
	v_lshlrev_b32_e32 v27, 2, v0
	v_xor_b32_e32 v0, 4, v228
	v_cmp_lt_i32_e32 vcc, v0, v8
	s_nop 1
	v_cndmask_b32_e32 v0, v228, v0, vcc
	v_lshlrev_b32_e32 v28, 2, v0
	v_xor_b32_e32 v0, 8, v228
	v_cmp_lt_i32_e32 vcc, v0, v8
	s_nop 1
	v_cndmask_b32_e32 v0, v228, v0, vcc
	v_lshlrev_b32_e32 v29, 2, v0
	v_lshlrev_b32_e32 v0, 5, v3
	v_xor_b32_e32 v3, 16, v228
	v_cmp_lt_i32_e32 vcc, v3, v8
	v_and_b32_e32 v0, 0x1e0, v0
	v_lshl_add_u64 v[4:5], s[4:5], 0, v[0:1]
	v_cndmask_b32_e32 v3, v228, v3, vcc
	v_lshlrev_b32_e32 v30, 2, v3
	v_xor_b32_e32 v3, 32, v228
	v_cmp_lt_i32_e32 vcc, v3, v8
	v_lshlrev_b32_e32 v0, 2, v16
	s_mov_b64 s[4:5], 0x30f00000
	v_cndmask_b32_e32 v3, v228, v3, vcc
	v_lshlrev_b32_e32 v31, 2, v3
	v_ashrrev_i32_e32 v3, 31, v2
	v_lshlrev_b64 v[10:11], 7, v[2:3]
	v_lshl_or_b32 v8, v9, 2, v10
	v_lshl_or_b32 v10, v16, 1, v10
	v_lshlrev_b64 v[12:13], 8, v[2:3]
	v_mov_b32_e32 v9, v11
	v_lshl_add_u64 v[10:11], v[10:11], 0, s[4:5]
	v_or_b32_e32 v12, v12, v0
	s_mov_b64 s[4:5], 0x25b00000
	v_lshlrev_b64 v[14:15], 12, v[2:3]
	v_lshl_add_u64 v[6:7], s[12:13], 0, v[0:1]
	v_lshl_add_u64 v[12:13], v[12:13], 0, s[4:5]
	v_lshl_or_b32 v14, v16, 4, v14
	s_mov_b64 s[4:5], 0
	global_load_dwordx2 v[176:177], v[4:5], off
	global_load_dwordx2 v[178:179], v[4:5], off offset:8
	global_load_dwordx2 v[180:181], v[4:5], off offset:16
	global_load_dwordx2 v[182:183], v[4:5], off offset:24
	global_load_dword v211, v[6:7], off
	s_waitcnt vmcnt(0) lgkmcnt(0)
.LBB0_322:
	v_lshl_add_u64 v[16:17], s[8:9], 0, v[14:15]
	v_add_co_u32_e32 v16, vcc, 0x28f00000, v16
	s_mov_b32 s2, 0x1100000
	s_nop 0
	v_addc_co_u32_e32 v17, vcc, 0, v17, vcc
	global_load_dwordx4 v[32:35], v[16:17], off
	global_load_dwordx4 v[184:187], v[16:17], off offset:1024
	global_load_dwordx4 v[188:191], v[16:17], off offset:2048
	global_load_dwordx4 v[192:195], v[16:17], off offset:3072
	v_lshl_add_u64 v[240:241], s[8:9], 0, v[12:13]
	global_load_dword v208, v[240:241], off
	v_lshl_add_u64 v[240:241], s[8:9], 0, v[8:9]
	v_add_co_u32_e32 v242, vcc, 0x1100000, v240
	s_nop 1
	v_addc_co_u32_e32 v243, vcc, 0, v241, vcc
	global_load_dword v209, v[242:243], off
	v_add_co_u32_e32 v242, vcc, 0x1300000, v240
	s_nop 1
	v_addc_co_u32_e32 v243, vcc, 0, v241, vcc
	global_load_dword v210, v[242:243], off
	v_add_u32_e32 v2, s52, v2
	v_lshl_add_u64 v[14:15], v[14:15], 0, s[30:31]
	s_waitcnt vmcnt(0) lgkmcnt(0)
	v_and_b32_e32 v23, 0xffff0000, v33
	v_and_b32_e32 v22, 0xffff0000, v32
	v_lshlrev_b32_e32 v25, 16, v33
	v_lshlrev_b32_e32 v24, 16, v32
	v_pk_mul_f32 v[18:19], v[22:23], v[22:23]
	v_lshlrev_b32_e32 v21, 16, v35
	v_pk_fma_f32 v[32:33], v[24:25], v[24:25], v[18:19]
	v_and_b32_e32 v19, 0xffff0000, v35
	v_add_f32_e32 v0, v32, v33
	v_mov_b32_e32 v32, v176
	v_mov_b32_e32 v33, v177
	v_and_b32_e32 v18, 0xffff0000, v34
	v_lshlrev_b32_e32 v20, 16, v34
	v_pk_mul_f32 v[34:35], v[18:19], v[18:19]
	s_nop 0
	v_pk_fma_f32 v[34:35], v[20:21], v[20:21], v[34:35]
	s_nop 0
	v_add_f32_e32 v0, v34, v0
	v_add_f32_e32 v0, v35, v0
	ds_bpermute_b32 v3, v26, v0
	s_waitcnt lgkmcnt(0)
	v_add_f32_e32 v0, v0, v3
	ds_bpermute_b32 v3, v27, v0
	s_waitcnt lgkmcnt(0)
	v_add_f32_e32 v0, v0, v3
	ds_bpermute_b32 v3, v28, v0
	s_waitcnt lgkmcnt(0)
	v_add_f32_e32 v0, v0, v3
	ds_bpermute_b32 v3, v29, v0
	s_waitcnt lgkmcnt(0)
	v_add_f32_e32 v0, v0, v3
	v_fmamk_f32 v0, v0, 0x3c000000, v207
	v_cmp_gt_f32_e32 vcc, s87, v0
	v_mul_f32_e32 v3, 0x4b800000, v0
	s_nop 0
	v_cndmask_b32_e32 v0, v0, v3, vcc
	v_rsq_f32_e32 v0, v0
	s_nop 0
	v_mul_f32_e32 v3, 0x45800000, v0
	v_cndmask_b32_e32 v0, v0, v3, vcc
	v_mul_f32_e32 v3, v0, v24
	v_mul_f32_e32 v22, v0, v22
	v_mul_f32_e32 v23, v0, v23
	v_mul_f32_e32 v18, v0, v18

	v_mul_f32_e32 v3, v32, v3
	v_mul_f32_e32 v22, v33, v22
	v_cvt_pk_bf16_f32 v22, v3, v22
	v_mul_f32_e32 v3, v0, v25
	v_mov_b32_e32 v24, v178
	v_mov_b32_e32 v25, v179
	v_mul_f32_e32 v23, v25, v23
	v_mul_f32_e32 v3, v24, v3
	v_cvt_pk_bf16_f32 v23, v3, v23
	v_mov_b32_e32 v24, v180
	v_mov_b32_e32 v25, v181
	v_mul_f32_e32 v3, v0, v20
	v_mul_f32_e32 v3, v24, v3
	v_mul_f32_e32 v18, v25, v18
	v_cvt_pk_bf16_f32 v24, v3, v18
	v_mul_f32_e32 v3, v0, v21
	v_mov_b32_e32 v20, v182
	v_mov_b32_e32 v21, v183
	v_mul_f32_e32 v0, v0, v19
	v_mul_f32_e32 v3, v20, v3
	v_mul_f32_e32 v0, v21, v0
	v_cvt_pk_bf16_f32 v25, v3, v0
	v_mov_b32_e32 v32, v184
	v_mov_b32_e32 v33, v185
	v_mov_b32_e32 v34, v186
	v_mov_b32_e32 v35, v187
	v_lshlrev_b32_e32 v21, 16, v35
	global_store_dwordx4 v[16:17], v[22:25], off
	v_lshlrev_b32_e32 v20, 16, v34
	s_nop 0
	v_and_b32_e32 v23, 0xffff0000, v33
	v_and_b32_e32 v22, 0xffff0000, v32
	v_lshlrev_b32_e32 v25, 16, v33
	v_lshlrev_b32_e32 v24, 16, v32
	v_pk_mul_f32 v[18:19], v[22:23], v[22:23]
	s_nop 0
	v_pk_fma_f32 v[32:33], v[24:25], v[24:25], v[18:19]
	v_and_b32_e32 v19, 0xffff0000, v35
	v_add_f32_e32 v0, v32, v33
	v_mov_b32_e32 v32, v176
	v_mov_b32_e32 v33, v177
	v_and_b32_e32 v18, 0xffff0000, v34
	v_pk_mul_f32 v[34:35], v[18:19], v[18:19]
	s_nop 0
	v_pk_fma_f32 v[34:35], v[20:21], v[20:21], v[34:35]
	s_nop 0
	v_add_f32_e32 v0, v34, v0
	v_add_f32_e32 v0, v35, v0
	ds_bpermute_b32 v3, v26, v0
	s_waitcnt lgkmcnt(0)
	v_add_f32_e32 v0, v0, v3
	ds_bpermute_b32 v3, v27, v0
	s_waitcnt lgkmcnt(0)
	v_add_f32_e32 v0, v0, v3
	ds_bpermute_b32 v3, v28, v0
	s_waitcnt lgkmcnt(0)
	v_add_f32_e32 v0, v0, v3
	ds_bpermute_b32 v3, v29, v0
	s_waitcnt lgkmcnt(0)
	v_add_f32_e32 v0, v0, v3
	v_fmamk_f32 v0, v0, 0x3c000000, v207
	v_cmp_gt_f32_e32 vcc, s87, v0
	v_mul_f32_e32 v3, 0x4b800000, v0
	s_nop 0
	v_cndmask_b32_e32 v0, v0, v3, vcc
	v_rsq_f32_e32 v0, v0
	s_nop 0
	v_mul_f32_e32 v3, 0x45800000, v0
	v_cndmask_b32_e32 v0, v0, v3, vcc
	v_mul_f32_e32 v3, v0, v24
	v_mul_f32_e32 v22, v0, v22
	v_mul_f32_e32 v23, v0, v23
	v_mul_f32_e32 v18, v0, v18

	v_mul_f32_e32 v3, v32, v3
	v_mul_f32_e32 v22, v33, v22
	v_cvt_pk_bf16_f32 v22, v3, v22
	v_mul_f32_e32 v3, v0, v25
	v_mov_b32_e32 v24, v178
	v_mov_b32_e32 v25, v179
	v_mul_f32_e32 v23, v25, v23
	v_mul_f32_e32 v3, v24, v3
	v_cvt_pk_bf16_f32 v23, v3, v23
	v_mov_b32_e32 v24, v180
	v_mov_b32_e32 v25, v181
	v_mul_f32_e32 v3, v0, v20
	v_mul_f32_e32 v3, v24, v3
	v_mul_f32_e32 v18, v25, v18
	v_cvt_pk_bf16_f32 v24, v3, v18
	v_mul_f32_e32 v3, v0, v21
	v_mov_b32_e32 v20, v182
	v_mov_b32_e32 v21, v183
	v_mul_f32_e32 v0, v0, v19
	v_mul_f32_e32 v3, v20, v3
	v_mul_f32_e32 v0, v21, v0
	v_cvt_pk_bf16_f32 v25, v3, v0
	v_mov_b32_e32 v32, v188
	v_mov_b32_e32 v33, v189
	v_mov_b32_e32 v34, v190
	v_mov_b32_e32 v35, v191
	v_lshlrev_b32_e32 v21, 16, v35
	global_store_dwordx4 v[16:17], v[22:25], off offset:1024
	v_lshlrev_b32_e32 v20, 16, v34
	s_nop 0
	v_and_b32_e32 v23, 0xffff0000, v33
	v_and_b32_e32 v22, 0xffff0000, v32
	v_lshlrev_b32_e32 v25, 16, v33
	v_lshlrev_b32_e32 v24, 16, v32
	v_pk_mul_f32 v[18:19], v[22:23], v[22:23]
	s_nop 0
	v_pk_fma_f32 v[32:33], v[24:25], v[24:25], v[18:19]
	v_and_b32_e32 v19, 0xffff0000, v35
	v_add_f32_e32 v0, v32, v33
	v_mov_b32_e32 v32, v176
	v_mov_b32_e32 v33, v177
	v_and_b32_e32 v18, 0xffff0000, v34
	v_pk_mul_f32 v[34:35], v[18:19], v[18:19]
	s_nop 0
	v_pk_fma_f32 v[34:35], v[20:21], v[20:21], v[34:35]
	s_nop 0
	v_add_f32_e32 v0, v34, v0
	v_add_f32_e32 v0, v35, v0
	ds_bpermute_b32 v3, v26, v0
	s_waitcnt lgkmcnt(0)
	v_add_f32_e32 v0, v0, v3
	ds_bpermute_b32 v3, v27, v0
	s_waitcnt lgkmcnt(0)
	v_add_f32_e32 v0, v0, v3
	ds_bpermute_b32 v3, v28, v0
	s_waitcnt lgkmcnt(0)
	v_add_f32_e32 v0, v0, v3
	ds_bpermute_b32 v3, v29, v0
	s_waitcnt lgkmcnt(0)
	v_add_f32_e32 v0, v0, v3
	v_fmamk_f32 v0, v0, 0x3c000000, v207
	v_cmp_gt_f32_e32 vcc, s87, v0
	v_mul_f32_e32 v3, 0x4b800000, v0
	s_nop 0
	v_cndmask_b32_e32 v0, v0, v3, vcc
	v_rsq_f32_e32 v0, v0
	s_nop 0
	v_mul_f32_e32 v3, 0x45800000, v0
	v_cndmask_b32_e32 v0, v0, v3, vcc
	v_mul_f32_e32 v3, v0, v24
	v_mul_f32_e32 v22, v0, v22
	v_mul_f32_e32 v23, v0, v23
	v_mul_f32_e32 v18, v0, v18

	v_mul_f32_e32 v3, v32, v3
	v_mul_f32_e32 v22, v33, v22
	v_cvt_pk_bf16_f32 v22, v3, v22
	v_mul_f32_e32 v3, v0, v25
	v_mov_b32_e32 v24, v178
	v_mov_b32_e32 v25, v179
	v_mul_f32_e32 v23, v25, v23
	v_mul_f32_e32 v3, v24, v3
	v_cvt_pk_bf16_f32 v23, v3, v23
	v_mov_b32_e32 v24, v180
	v_mov_b32_e32 v25, v181
	v_mul_f32_e32 v3, v0, v20
	v_mul_f32_e32 v3, v24, v3
	v_mul_f32_e32 v18, v25, v18
	v_cvt_pk_bf16_f32 v24, v3, v18
	v_mul_f32_e32 v3, v0, v21
	v_mov_b32_e32 v20, v182
	v_mov_b32_e32 v21, v183
	v_mul_f32_e32 v0, v0, v19
	v_mul_f32_e32 v3, v20, v3
	v_mul_f32_e32 v0, v21, v0
	v_cvt_pk_bf16_f32 v25, v3, v0
	v_mov_b32_e32 v32, v192
	v_mov_b32_e32 v33, v193
	v_mov_b32_e32 v34, v194
	v_mov_b32_e32 v35, v195
	v_lshlrev_b32_e32 v21, 16, v35
	global_store_dwordx4 v[16:17], v[22:25], off offset:2048
	v_lshlrev_b32_e32 v20, 16, v34
	s_nop 0
	v_and_b32_e32 v23, 0xffff0000, v33
	v_and_b32_e32 v22, 0xffff0000, v32
	v_lshlrev_b32_e32 v25, 16, v33
	v_lshlrev_b32_e32 v24, 16, v32
	v_pk_mul_f32 v[18:19], v[22:23], v[22:23]
	s_nop 0
	v_pk_fma_f32 v[32:33], v[24:25], v[24:25], v[18:19]
	v_and_b32_e32 v19, 0xffff0000, v35
	v_add_f32_e32 v0, v32, v33
	v_mov_b32_e32 v32, v176
	v_mov_b32_e32 v33, v177
	v_and_b32_e32 v18, 0xffff0000, v34
	v_pk_mul_f32 v[34:35], v[18:19], v[18:19]
	s_nop 0
	v_pk_fma_f32 v[34:35], v[20:21], v[20:21], v[34:35]
	s_nop 0
	v_add_f32_e32 v0, v34, v0
	v_add_f32_e32 v0, v35, v0
	ds_bpermute_b32 v3, v26, v0
	s_waitcnt lgkmcnt(0)
	v_add_f32_e32 v0, v0, v3
	ds_bpermute_b32 v3, v27, v0
	s_waitcnt lgkmcnt(0)
	v_add_f32_e32 v0, v0, v3
	ds_bpermute_b32 v3, v28, v0
	s_waitcnt lgkmcnt(0)
	v_add_f32_e32 v0, v0, v3
	ds_bpermute_b32 v3, v29, v0
	s_waitcnt lgkmcnt(0)
	v_add_f32_e32 v0, v0, v3
	v_fmamk_f32 v0, v0, 0x3c000000, v207
	v_cmp_gt_f32_e32 vcc, s87, v0
	v_mul_f32_e32 v3, 0x4b800000, v0
	s_nop 0
	v_cndmask_b32_e32 v0, v0, v3, vcc
	v_rsq_f32_e32 v0, v0
	s_nop 0
	v_mul_f32_e32 v3, 0x45800000, v0
	v_cndmask_b32_e32 v0, v0, v3, vcc
	v_mul_f32_e32 v3, v0, v24
	v_mul_f32_e32 v22, v0, v22
	v_mul_f32_e32 v23, v0, v23
	v_mul_f32_e32 v18, v0, v18

	v_mul_f32_e32 v3, v32, v3
	v_mul_f32_e32 v22, v33, v22
	v_cvt_pk_bf16_f32 v22, v3, v22
	v_mul_f32_e32 v3, v0, v25
	v_mov_b32_e32 v24, v178
	v_mov_b32_e32 v25, v179
	v_mul_f32_e32 v23, v25, v23
	v_mul_f32_e32 v3, v24, v3
	v_cvt_pk_bf16_f32 v23, v3, v23
	v_mov_b32_e32 v24, v180
	v_mov_b32_e32 v25, v181
	v_mul_f32_e32 v3, v0, v20
	v_mul_f32_e32 v3, v24, v3
	v_mul_f32_e32 v18, v25, v18
	v_cvt_pk_bf16_f32 v24, v3, v18
	v_mul_f32_e32 v3, v0, v21
	v_mov_b32_e32 v20, v182
	v_mov_b32_e32 v21, v183
	v_mul_f32_e32 v0, v0, v19
	v_mul_f32_e32 v3, v20, v3
	v_mul_f32_e32 v0, v21, v0
	v_cvt_pk_bf16_f32 v25, v3, v0
	global_store_dwordx4 v[16:17], v[22:25], off offset:3072
	v_lshl_add_u64 v[16:17], s[8:9], 0, v[12:13]
	v_mov_b32_e32 v0, v208
	v_lshl_add_u64 v[12:13], v[12:13], 0, s[18:19]
	s_nop 0
	v_mul_f32_e32 v3, v0, v0
	ds_bpermute_b32 v3, v26, v3
	s_waitcnt lgkmcnt(0)
	v_fmac_f32_e32 v3, v0, v0
	ds_bpermute_b32 v16, v27, v3
	s_waitcnt lgkmcnt(0)
	v_add_f32_e32 v3, v3, v16
	ds_bpermute_b32 v16, v28, v3
	s_waitcnt lgkmcnt(0)
	v_add_f32_e32 v3, v3, v16
	ds_bpermute_b32 v16, v29, v3
	s_waitcnt lgkmcnt(0)
	v_add_f32_e32 v3, v3, v16
	ds_bpermute_b32 v16, v30, v3
	s_waitcnt lgkmcnt(0)
	v_add_f32_e32 v3, v3, v16
	ds_bpermute_b32 v16, v31, v3
	s_waitcnt lgkmcnt(0)
	v_add_f32_e32 v3, v3, v16
	v_fmamk_f32 v3, v3, 0x3c800000, v207
	v_cmp_gt_f32_e32 vcc, s87, v3
	v_mul_f32_e32 v16, 0x4b800000, v3
	s_nop 0
	v_cndmask_b32_e32 v3, v3, v16, vcc
	v_rsq_f32_e32 v3, v3
	s_nop 0
	v_mul_f32_e32 v16, 0x45800000, v3
	v_cndmask_b32_e32 v3, v3, v16, vcc
	v_mul_f32_e32 v0, v0, v3
	v_mov_b32_e32 v3, v211
	v_lshl_add_u64 v[16:17], s[8:9], 0, v[8:9]
	v_add_co_u32_e32 v18, vcc, s2, v16
	s_mov_b32 s2, 0x1300000
	s_nop 0
	v_addc_co_u32_e32 v19, vcc, 0, v17, vcc
	v_add_co_u32_e32 v16, vcc, s2, v16
	v_mov_b32_e32 v18, v209
	s_nop 0
	v_addc_co_u32_e32 v17, vcc, 0, v17, vcc
	v_mov_b32_e32 v16, v210
	s_movk_i32 s2, 0x3fff
	v_cmp_lt_i32_e32 vcc, s2, v2
	v_lshl_add_u64 v[8:9], v[8:9], 0, s[14:15]
	s_or_b64 s[4:5], vcc, s[4:5]
	s_waitcnt lgkmcnt(0)
	v_mul_f32_e32 v0, v3, v0
	ds_bpermute_b32 v3, v31, v0
	s_waitcnt lgkmcnt(0)
	v_mul_f32_e32 v3, v16, v3
	v_cndmask_b32_e64 v3, v3, -v3, s[36:37]
	v_fmac_f32_e32 v3, v18, v0
	v_bfe_u32 v0, v3, 16, 1
	v_add3_u32 v0, v3, v0, s10
	v_lshl_add_u64 v[16:17], s[8:9], 0, v[10:11]
	v_lshl_add_u64 v[10:11], v[10:11], 0, s[14:15]
	global_store_short_d16_hi v[16:17], v0, off
	s_andn2_b64 exec, exec, s[4:5]
	s_cbranch_execnz .LBB0_322
